# P0 workgroup 0: the six serial wg_absmax passes for the softmax-shift constants rewritten by hand (all loads in flight at once, interleaved wave-max butterflies, one barrier); on top of v90
# speedup vs baseline: 1.0069x; 1.0060x over previous
; __device__ __forceinline__ float wave_max(float v) { v = fmaxf(v, dpp_mov<0xB1>(v)); v = fmaxf(v, dpp_mov<0x4E>(v)); v = fmaxf(v, dpp_mov<0x141>(v)); v = fmaxf(v, dpp_mov<0x140>(v)); v = max_x16(v); return max_x32(v); }
; #define LAS __attribute__((address_space(3)))
; __device__ __forceinline__ float wg_absmax(const float* p, int n, LAS float* scr, int tid) {
;     float m = 0.f;
;     for (int i = tid; i < n; i += NWAVES * 64) m = fmaxf(m, fabsf(p[i]));
;     m = wave_max(m);
;     __syncthreads();
;     if ((tid & 63) == 0) scr[tid >> 6] = m;
;     __syncthreads();
; __global__ void __launch_bounds__(NWAVES * 64, 2) fwd_kernel(Args args) {
;     ...
;         if (blockIdx.x == 0) {
;             LAS float* scr0 = (LAS float*)(F.lds + RING_OFF + 8 * 16384);
;             const float ca = 64.0f * QSCALE * att::wg_absmax(args.in[4], 192, scr0, F.tid) * att::wg_absmax(args.in[5], 192, scr0, F.tid) + LOG2E * att::wg_absmax(args.in[6], 48 * 32, scr0, F.tid);
;             const float cb = 64.0f * QSCALE * att::wg_absmax(args.in[9], 64, scr0, F.tid) * att::wg_absmax(args.in[10], 64, scr0, F.tid) + LOG2E * att::wg_absmax(args.in[11], NH * 15 * 31, scr0, F.tid);
.LBB0_63:
	v_mov_b32_e32 v0, 0
	v_mov_b32_e32 v1, 0
	v_mov_b32_e32 v2, 0
	v_mov_b32_e32 v3, 0
	v_mov_b32_e32 v4, 0
	v_mov_b32_e32 v5, 0
	v_mov_b32_e32 v6, 0
	v_mov_b32_e32 v7, 0
	v_mov_b32_e32 v8, 0
	v_mov_b32_e32 v9, 0
	v_mov_b32_e32 v10, 0
	v_mov_b32_e32 v11, 0
	v_mov_b32_e32 v12, 0
	v_mov_b32_e32 v13, 0
	v_mov_b32_e32 v14, 0
	v_mov_b32_e32 v15, 0
	v_mov_b32_e32 v16, 0
	v_mov_b32_e32 v17, 0
	v_mov_b32_e32 v18, 0
	v_mov_b32_e32 v19, 0
	v_mov_b32_e32 v20, 0
	v_mov_b32_e32 v21, 0
	v_lshlrev_b32_e32 v22, 2, v64
	v_readlane_b32 s8, v253, 8
	v_readlane_b32 s9, v253, 9
	v_readlane_b32 s10, v253, 10
	v_readlane_b32 s11, v253, 11
	v_readlane_b32 s12, v253, 12
	v_readlane_b32 s13, v253, 13
	v_cmp_gt_u32_e32 vcc, 0xc0, v64
	s_and_saveexec_b64 s[0:1], vcc
	global_load_dword v0, v22, s[52:53]
	global_load_dword v1, v22, s[54:55]
	s_mov_b64 exec, s[0:1]
	global_load_dword v2, v22, s[56:57]
	global_load_dword v3, v22, s[56:57] offset:2048
	v_add_u32_e32 v23, 0x1000, v22
	global_load_dword v4, v23, s[56:57]
	v_cmp_gt_u32_e32 vcc, 64, v64
	s_and_saveexec_b64 s[0:1], vcc
	global_load_dword v5, v22, s[8:9]
	global_load_dword v6, v22, s[10:11]
	s_mov_b64 exec, s[0:1]
	v_mov_b32_e32 v23, v22
	global_load_dword v7, v23, s[12:13]
	global_load_dword v8, v23, s[12:13] offset:2048
	v_add_u32_e32 v23, 0x1000, v23
	global_load_dword v9, v23, s[12:13]
	global_load_dword v10, v23, s[12:13] offset:2048
	v_add_u32_e32 v23, 0x1000, v23
	global_load_dword v11, v23, s[12:13]
	global_load_dword v12, v23, s[12:13] offset:2048
	v_add_u32_e32 v23, 0x1000, v23
	global_load_dword v13, v23, s[12:13]
	global_load_dword v14, v23, s[12:13] offset:2048
	v_add_u32_e32 v23, 0x1000, v23
	global_load_dword v15, v23, s[12:13]
	global_load_dword v16, v23, s[12:13] offset:2048
	v_add_u32_e32 v23, 0x1000, v23
	global_load_dword v17, v23, s[12:13]
	global_load_dword v18, v23, s[12:13] offset:2048
	v_add_u32_e32 v23, 0x1000, v23
	global_load_dword v19, v23, s[12:13]
	global_load_dword v20, v23, s[12:13] offset:2048
	v_add_u32_e32 v23, 0x1000, v23
	v_cmp_gt_u32_e32 vcc, 0x110, v64
	s_and_saveexec_b64 s[0:1], vcc
	global_load_dword v21, v23, s[12:13]
	s_mov_b64 exec, s[0:1]
	s_waitcnt vmcnt(0)
	v_max_f32_e64 v24, |v0|, |v0|
	v_max_f32_e64 v25, |v1|, |v1|
	v_max_f32_e64 v26, |v2|, |v3|
	v_max_f32_e64 v27, |v5|, |v5|
	v_max_f32_e64 v28, |v6|, |v6|
	v_max_f32_e64 v29, |v7|, |v8|
	v_max_f32_e64 v26, v26, |v4|
	v_max_f32_e64 v29, v29, |v9|
	v_max_f32_e64 v29, v29, |v10|
	v_max_f32_e64 v29, v29, |v11|
	v_max_f32_e64 v29, v29, |v12|
	v_max_f32_e64 v29, v29, |v13|
	v_max_f32_e64 v29, v29, |v14|
	v_max_f32_e64 v29, v29, |v15|
	v_max_f32_e64 v29, v29, |v16|
	v_max_f32_e64 v29, v29, |v17|
	v_max_f32_e64 v29, v29, |v18|
	v_max_f32_e64 v29, v29, |v19|
	v_max_f32_e64 v29, v29, |v20|
	v_max_f32_e64 v29, v29, |v21|
	s_nop 1
	v_mov_b32_dpp v30, v24 quad_perm:[1,0,3,2] row_mask:0xf bank_mask:0xf bound_ctrl:1
	v_mov_b32_dpp v31, v25 quad_perm:[1,0,3,2] row_mask:0xf bank_mask:0xf bound_ctrl:1
	v_mov_b32_dpp v32, v26 quad_perm:[1,0,3,2] row_mask:0xf bank_mask:0xf bound_ctrl:1
	v_mov_b32_dpp v33, v27 quad_perm:[1,0,3,2] row_mask:0xf bank_mask:0xf bound_ctrl:1
	v_mov_b32_dpp v34, v28 quad_perm:[1,0,3,2] row_mask:0xf bank_mask:0xf bound_ctrl:1
	v_mov_b32_dpp v35, v29 quad_perm:[1,0,3,2] row_mask:0xf bank_mask:0xf bound_ctrl:1
	v_max_f32_e32 v24, v24, v30
	v_max_f32_e32 v25, v25, v31
	v_max_f32_e32 v26, v26, v32
	v_max_f32_e32 v27, v27, v33
	v_max_f32_e32 v28, v28, v34
	v_max_f32_e32 v29, v29, v35
	s_nop 1
	v_mov_b32_dpp v30, v24 quad_perm:[2,3,0,1] row_mask:0xf bank_mask:0xf bound_ctrl:1
	v_mov_b32_dpp v31, v25 quad_perm:[2,3,0,1] row_mask:0xf bank_mask:0xf bound_ctrl:1
	v_mov_b32_dpp v32, v26 quad_perm:[2,3,0,1] row_mask:0xf bank_mask:0xf bound_ctrl:1
	v_mov_b32_dpp v33, v27 quad_perm:[2,3,0,1] row_mask:0xf bank_mask:0xf bound_ctrl:1
	v_mov_b32_dpp v34, v28 quad_perm:[2,3,0,1] row_mask:0xf bank_mask:0xf bound_ctrl:1
	v_mov_b32_dpp v35, v29 quad_perm:[2,3,0,1] row_mask:0xf bank_mask:0xf bound_ctrl:1
	v_max_f32_e32 v24, v24, v30
	v_max_f32_e32 v25, v25, v31
	v_max_f32_e32 v26, v26, v32
	v_max_f32_e32 v27, v27, v33
	v_max_f32_e32 v28, v28, v34
	v_max_f32_e32 v29, v29, v35
	s_nop 1
	v_mov_b32_dpp v30, v24 row_half_mirror row_mask:0xf bank_mask:0xf bound_ctrl:1
	v_mov_b32_dpp v31, v25 row_half_mirror row_mask:0xf bank_mask:0xf bound_ctrl:1
	v_mov_b32_dpp v32, v26 row_half_mirror row_mask:0xf bank_mask:0xf bound_ctrl:1
	v_mov_b32_dpp v33, v27 row_half_mirror row_mask:0xf bank_mask:0xf bound_ctrl:1
	v_mov_b32_dpp v34, v28 row_half_mirror row_mask:0xf bank_mask:0xf bound_ctrl:1
	v_mov_b32_dpp v35, v29 row_half_mirror row_mask:0xf bank_mask:0xf bound_ctrl:1
	v_max_f32_e32 v24, v24, v30
	v_max_f32_e32 v25, v25, v31
	v_max_f32_e32 v26, v26, v32
	v_max_f32_e32 v27, v27, v33
	v_max_f32_e32 v28, v28, v34
	v_max_f32_e32 v29, v29, v35
	s_nop 1
	v_mov_b32_dpp v30, v24 row_mirror row_mask:0xf bank_mask:0xf bound_ctrl:1
	v_mov_b32_dpp v31, v25 row_mirror row_mask:0xf bank_mask:0xf bound_ctrl:1
	v_mov_b32_dpp v32, v26 row_mirror row_mask:0xf bank_mask:0xf bound_ctrl:1
	v_mov_b32_dpp v33, v27 row_mirror row_mask:0xf bank_mask:0xf bound_ctrl:1
	v_mov_b32_dpp v34, v28 row_mirror row_mask:0xf bank_mask:0xf bound_ctrl:1
	v_mov_b32_dpp v35, v29 row_mirror row_mask:0xf bank_mask:0xf bound_ctrl:1
	v_max_f32_e32 v24, v24, v30
	v_max_f32_e32 v25, v25, v31
	v_max_f32_e32 v26, v26, v32
	v_max_f32_e32 v27, v27, v33
	v_max_f32_e32 v28, v28, v34
	v_max_f32_e32 v29, v29, v35
	v_mov_b32_e32 v30, v24
	v_mov_b32_e32 v31, v25
	v_mov_b32_e32 v32, v26
	v_mov_b32_e32 v33, v27
	v_mov_b32_e32 v34, v28
	v_mov_b32_e32 v35, v29
	s_nop 1
	v_permlane16_swap_b32_e32 v24, v30
	v_permlane16_swap_b32_e32 v25, v31
	v_permlane16_swap_b32_e32 v26, v32
	v_permlane16_swap_b32_e32 v27, v33
	v_permlane16_swap_b32_e32 v28, v34
	v_permlane16_swap_b32_e32 v29, v35
	s_nop 1
	v_max_f32_e32 v24, v24, v30
	v_max_f32_e32 v25, v25, v31
	v_max_f32_e32 v26, v26, v32
	v_max_f32_e32 v27, v27, v33
	v_max_f32_e32 v28, v28, v34
	v_max_f32_e32 v29, v29, v35
	v_mov_b32_e32 v30, v24
	v_mov_b32_e32 v31, v25
	v_mov_b32_e32 v32, v26
	v_mov_b32_e32 v33, v27
	v_mov_b32_e32 v34, v28
	v_mov_b32_e32 v35, v29
	s_nop 1
	v_permlane32_swap_b32_e32 v24, v30
	v_permlane32_swap_b32_e32 v25, v31
	v_permlane32_swap_b32_e32 v26, v32
	v_permlane32_swap_b32_e32 v27, v33
	v_permlane32_swap_b32_e32 v28, v34
	v_permlane32_swap_b32_e32 v29, v35
	s_nop 1
	v_max_f32_e32 v24, v24, v30
	v_max_f32_e32 v25, v25, v31
	v_max_f32_e32 v26, v26, v32
	v_max_f32_e32 v27, v27, v33
	v_max_f32_e32 v28, v28, v34
	v_max_f32_e32 v29, v29, v35
	v_and_b32_e32 v36, 63, v64
	v_lshrrev_b32_e32 v37, 6, v64
	v_lshlrev_b32_e32 v37, 2, v37
	v_add_u32_e32 v37, 0x20000, v37
	v_cmp_eq_u32_e32 vcc, 0, v36
	s_and_saveexec_b64 s[0:1], vcc
	ds_write_b32 v37, v24
	ds_write_b32 v37, v25 offset:32
	ds_write_b32 v37, v26 offset:64
	ds_write_b32 v37, v27 offset:96
	ds_write_b32 v37, v28 offset:128
	ds_write_b32 v37, v29 offset:160
	s_mov_b64 exec, s[0:1]
	s_waitcnt lgkmcnt(0)
	s_barrier
; __device__ __forceinline__ float wg_absmax(const float* p, int n, LAS float* scr, int tid) {
;     ...
;     float r = scr[0];
; #pragma unroll
;     for (int i = 1; i < NWAVES; ++i) r = fmaxf(r, scr[i]);
;     return r;
; __global__ void __launch_bounds__(NWAVES * 64, 2) fwd_kernel(Args args) {
;     ...
;             const float ca = 64.0f * QSCALE * att::wg_absmax(args.in[4], 192, scr0, F.tid) * att::wg_absmax(args.in[5], 192, scr0, F.tid) + LOG2E * att::wg_absmax(args.in[6], 48 * 32, scr0, F.tid);
;             const float cb = 64.0f * QSCALE * att::wg_absmax(args.in[9], 64, scr0, F.tid) * att::wg_absmax(args.in[10], 64, scr0, F.tid) + LOG2E * att::wg_absmax(args.in[11], NH * 15 * 31, scr0, F.tid);
;             if (F.tid == 0) { float* cs = (float*)(ws + WS_CSHIFT); cs[0] = ca; cs[1] = cb; }
	v_mov_b32_e32 v48, 0x20000
	ds_read_b128 v[0:3], v48
	ds_read_b128 v[4:7], v48 offset:16
	ds_read_b128 v[8:11], v48 offset:32
	ds_read_b128 v[12:15], v48 offset:48
	ds_read_b128 v[16:19], v48 offset:64
	ds_read_b128 v[20:23], v48 offset:80
	ds_read_b128 v[24:27], v48 offset:96
	ds_read_b128 v[28:31], v48 offset:112
	ds_read_b128 v[32:35], v48 offset:128
	ds_read_b128 v[36:39], v48 offset:144
	ds_read_b128 v[40:43], v48 offset:160
	ds_read_b128 v[44:47], v48 offset:176
	s_waitcnt lgkmcnt(0)
	v_max3_f32 v0, v0, v1, v2
	v_max3_f32 v4, v3, v4, v5
	v_max3_f32 v0, v0, v6, v7
	v_max_f32_e32 v0, v0, v4
	v_max3_f32 v8, v8, v9, v10
	v_max3_f32 v12, v11, v12, v13
	v_max3_f32 v8, v8, v14, v15
	v_max_f32_e32 v8, v8, v12
	v_max3_f32 v16, v16, v17, v18
	v_max3_f32 v20, v19, v20, v21
	v_max3_f32 v16, v16, v22, v23
	v_max_f32_e32 v16, v16, v20
	v_max3_f32 v24, v24, v25, v26
	v_max3_f32 v28, v27, v28, v29
	v_max3_f32 v24, v24, v30, v31
	v_max_f32_e32 v24, v24, v28
	v_max3_f32 v32, v32, v33, v34
	v_max3_f32 v36, v35, v36, v37
	v_max3_f32 v32, v32, v38, v39
	v_max_f32_e32 v32, v32, v36
	v_max3_f32 v40, v40, v41, v42
	v_max3_f32 v44, v43, v44, v45
	v_max3_f32 v40, v40, v46, v47
	v_max_f32_e32 v40, v40, v44
	v_mul_f32_e32 v0, 0x4138aa3b, v0
	v_mul_f32_e32 v24, 0x4138aa3b, v24
	v_mul_f32_e32 v16, 0x3fb8aa3b, v16
	v_mul_f32_e32 v40, 0x3fb8aa3b, v40
	v_fma_f32 v0, v0, v8, v16
	v_fma_f32 v1, v24, v32, v40
	v_readlane_b32 s4, v253, 20
	v_readlane_b32 s5, v253, 21
	v_mov_b32_e32 v2, 0
	v_cmp_eq_u32_e32 vcc, 0, v64
	s_and_saveexec_b64 s[0:1], vcc
	s_nop 3
	global_store_dwordx2 v2, v[0:1], s[4:5]
